# attention V^T LDS tile: rows with d&8 shifted by 8 B -> conflict-free ds_read2_b64 fragment reads
# speedup vs baseline: 1.0570x; 1.0070x over previous
.LBB0_753:
	s_and_b32 s8, s13, 7
	s_cmp_lt_u32 s14, 2
	s_cselect_b64 s[6:7], -1, 0
	v_cndmask_b32_e64 v0, 0, 1, s[6:7]
	s_nop 0
	v_readfirstlane_b32 s6, v0
	s_lshr_b32 s9, s15, s6
	s_cmp_eq_u32 s14, 2
	s_cselect_b32 s6, 4, 8
	s_cmp_lg_u32 s14, 1
	s_cselect_b32 s10, s6, 2
	s_and_b64 s[6:7], s[0:1], exec
	s_cselect_b32 s6, 0, s10
	s_lshl_b32 s7, s14, 5
	s_lshl_b32 s10, s8, 2
	s_or_b32 s7, s7, s10
	s_or_b32 s7, s7, s15
	s_mul_i32 s7, s7, 0x48000
	s_add_u32 s54, s21, s7
	s_addc_u32 s55, s24, 0
	s_add_i32 s6, s6, s9
	s_lshl_b32 s6, s6, 3
	s_or_b32 s6, s6, s8
	s_mul_i32 s66, s6, 0x24000
	s_lshl_b64 s[6:7], s[66:67], 1
	s_add_u32 s50, s25, s6
	s_addc_u32 s51, s26, s7
	s_add_u32 s52, s27, s6
	s_addc_u32 s53, s28, s7
	s_lshl_b32 s6, s8, 8
	s_lshl_b32 s7, s8, 11
	s_bitset1_b32 s6, 14
	s_add_i32 s7, s7, s12
	s_and_b64 s[4:5], exec, s[4:5]
	s_cselect_b32 s4, s6, s7
	s_lshl_b32 s4, s4, 11
	s_add_u32 s4, s30, s4
	s_addc_u32 s5, s34, 0
	s_lshl_b32 s6, s14, 9
	s_add_u32 s4, s4, s6
	s_addc_u32 s5, s5, 0
	s_lshl_b32 s6, s15, 7
	s_add_u32 s16, s4, s6
	s_addc_u32 s17, s5, 0
	s_add_i32 s6, s12, s35
	s_cmp_lg_u32 s14, 3
	s_mov_b64 s[4:5], -1
	s_cbranch_scc0 .LBB0_809
	v_mov_b32_e32 v0, v216
	s_lshl_b32 s4, s64, 7
	v_ashrrev_i32_e32 v152, 3, v0
	v_and_b32_e32 v145, 15, v0
	v_bfe_u32 v5, v0, 4, 2
	v_lshlrev_b32_e32 v6, 3, v0
	v_bfe_u32 v0, v0, 1, 6
	v_and_b32_e32 v1, 0x7ffffff0, v152
	v_mul_u32_u24_e32 v0, 0x48, v0
	v_and_or_b32 v1, v6, 8, v1
	v_add_lshl_u32 v4, v1, v0, 1
	v_or_b32_e32 v0, s6, v145
	v_ashrrev_i32_e32 v1, 31, v0
	v_lshlrev_b64 v[2:3], 7, v[0:1]
	v_lshl_add_u64 v[2:3], s[54:55], 0, v[2:3]
	v_lshlrev_b32_e32 v12, 4, v5
	v_lshl_add_u64 v[2:3], v[2:3], 0, v[12:13]
	global_load_dwordx4 v[16:19], v[2:3], off
	global_load_dwordx4 v[20:23], v[2:3], off offset:64
	v_or_b32_e32 v2, 16, v0
	s_add_u32 s4, s52, s4
	v_ashrrev_i32_e32 v7, 31, v6
	v_ashrrev_i32_e32 v3, 31, v2
	s_addc_u32 s5, s53, 0
	v_lshlrev_b64 v[14:15], 1, v[6:7]
	v_lshlrev_b64 v[8:9], 7, v[2:3]
	s_waitcnt vmcnt(11)
	v_lshl_add_u64 v[32:33], s[4:5], 0, v[14:15]
	s_or_b32 s4, s64, 64
	v_lshl_add_u64 v[8:9], s[54:55], 0, v[8:9]
	s_cmp_gt_i32 s62, 1
	v_lshl_add_u64 v[8:9], v[8:9], 0, v[12:13]
	s_cselect_b32 s4, s4, s64
	global_load_dwordx4 v[24:27], v[8:9], off
	global_load_dwordx4 v[28:31], v[8:9], off offset:64
	v_add_u32_e32 v8, s64, v152
	global_load_dwordx4 v[40:43], v[32:33], off
	v_add_u32_e32 v32, s4, v152
	v_ashrrev_i32_e32 v9, 31, v8
	v_ashrrev_i32_e32 v33, 31, v32
	s_lshl_b32 s4, s4, 7
	v_and_b32_e32 v1, 56, v6
	v_lshlrev_b64 v[8:9], 7, v[8:9]
	v_lshlrev_b64 v[32:33], 7, v[32:33]
	s_add_u32 s4, s52, s4
	v_lshl_add_u64 v[8:9], s[50:51], 0, v[8:9]
	v_lshlrev_b32_e32 v12, 1, v1
	v_lshl_add_u64 v[32:33], s[50:51], 0, v[32:33]
	s_addc_u32 s5, s53, 0
	v_lshl_add_u64 v[8:9], v[8:9], 0, v[12:13]
	v_lshl_add_u64 v[32:33], v[32:33], 0, v[12:13]
	v_lshl_add_u64 v[14:15], s[4:5], 0, v[14:15]
	global_load_dwordx4 v[8:11], v[8:9], off
	v_mul_lo_u32 v3, v152, s87
	global_load_dwordx4 v[32:35], v[32:33], off
	v_add_lshl_u32 v3, v3, v1, 1
	global_load_dwordx4 v[36:39], v[14:15], off
	v_add_u32_e32 v153, 0, v3
	v_lshrrev_b32_e32 v252, 1, v216
	v_and_b32_e32 v252, 8, v252
	v_add_u32_e32 v154, v4, v252
	v_add_u32_e32 v250, 0x2400, v154
	v_add_u32_e32 v251, 0x6c00, v154
	s_mov_b64 s[4:5], -1
	s_cmp_gt_i32 s62, 0
	v_lshlrev_b32_e32 v144, 2, v5
	s_waitcnt vmcnt(2)
	ds_write_b128 v153, v[8:11]
	ds_write2_b64 v250, v[40:41], v[42:43] offset1:1
	s_waitcnt lgkmcnt(0)
	s_barrier
	s_cbranch_scc1 .LBB0_756
	v_lshlrev_b32_e32 v1, 2, v5
	s_mov_b64 s[4:5], 0
.LBB0_756:
	v_cndmask_b32_e64 v4, 0, 1.0, s[0:1]
	s_andn2_b64 vcc, exec, s[4:5]
	v_mov_b32_e32 v11, 0
	s_cbranch_vccnz .LBB0_802
	v_writelane_b32 v254, s16, 53
	v_lshlrev_b32_e32 v1, 3, v5
	v_lshl_add_u64 v[146:147], s[50:51], 0, v[12:13]
	v_mov_b32_e32 v9, 0x480
	v_mov_b32_e32 v11, 0x900
	v_mov_b32_e32 v12, 0xd80
	v_writelane_b32 v254, s17, 54
	v_lshl_add_u64 v[148:149], v[6:7], 1, s[52:53]
	v_or_b32_e32 v3, 32, v1
	v_mul_u32_u24_e32 v7, 0x48, v145
	v_mad_u32_u24 v9, v145, s87, v9
	v_mad_u32_u24 v11, v145, s87, v11
	v_mad_u32_u24 v12, v145, s87, v12
	s_ashr_i32 s65, s6, 6
	v_and_b32_e32 v155, 47, v0
	v_writelane_b32 v254, s66, 55
	v_add_u32_e32 v6, 0, v1
	v_add_lshl_u32 v8, v1, v7, 1
	v_add_lshl_u32 v7, v3, v7, 1
	v_add_lshl_u32 v10, v9, v1, 1
	v_add_lshl_u32 v9, v3, v9, 1
	v_add_lshl_u32 v40, v11, v1, 1
	v_add_lshl_u32 v11, v3, v11, 1
	v_add_lshl_u32 v1, v12, v1, 1
	v_add_lshl_u32 v3, v3, v12, 1
	s_max_i32 s0, s65, 4
	v_sub_u32_e64 v12, v155, 8 clamp
	v_writelane_b32 v254, s67, 56
	s_add_i32 s0, s0, -4
	v_sub_u32_e32 v12, v12, v144
	v_writelane_b32 v254, s6, 57
	s_min_u32 s66, s0, 24
	v_cmp_lt_i32_e64 s[0:1], 0, v12
	v_add_u32_e32 v14, 16, v12
	v_and_b32_e32 v156, 63, v2
	v_writelane_b32 v254, s0, 17
	v_add_u32_e32 v2, -8, v156
	v_min_u32_e32 v2, 48, v2
	v_writelane_b32 v254, s1, 18
	v_cmp_lt_i32_e64 s[0:1], 1, v12
	v_sub_u32_e32 v2, v2, v144
	v_mov_b32_e32 v15, v13
	v_writelane_b32 v254, s0, 19
	s_xor_b64 s[58:59], s[2:3], -1
	v_cmp_lt_i32_e64 s[74:75], 17, v2
	v_writelane_b32 v254, s1, 20
	v_cmp_lt_i32_e64 s[0:1], 2, v12
	v_cmp_lt_i32_e64 s[78:79], 18, v2
	v_cmp_lt_i32_e64 s[82:83], 19, v2
	v_writelane_b32 v254, s0, 15
	v_cmp_lt_i32_e64 s[86:87], 32, v2
	v_cmp_lt_i32_e64 s[90:91], 33, v2
	v_writelane_b32 v254, s1, 16
	v_cmp_lt_i32_e64 s[0:1], 3, v12
	v_cmp_lt_i32_e64 s[94:95], 34, v2
	v_cmp_lt_i32_e64 s[16:17], 35, v2
	v_writelane_b32 v254, s0, 58
	s_lshl_b32 s2, s63, 6
	v_add_u32_e32 v159, 0, v8
	v_writelane_b32 v254, s1, 59
	v_cmp_lt_i32_e64 s[0:1], 16, v12
	v_add_u32_e32 v161, 0, v10
	v_add_u32_e32 v162, 0, v9
	v_writelane_b32 v254, s0, 60
	v_add_u32_e32 v164, 0, v11
	v_mov_b32_e32 v151, v150
	v_writelane_b32 v254, s1, 61
	v_cmp_gt_u32_e64 s[0:1], 17, v14
	s_mov_b32 s67, 0
	s_mov_b32 s68, 3
	v_writelane_b32 v254, s0, 62
	s_add_i32 s69, s66, 8
	v_lshl_add_u32 v157, v5, 4, 0
	v_writelane_b32 v254, s1, 63
	v_cmp_lt_i32_e64 s[0:1], 17, v12
	s_sub_i32 s70, s33, s2
	v_sub_u32_e32 v158, v144, v0
	v_writelane_b32 v255, s0, 0
	v_add_u32_e32 v160, 0, v7
	v_add_u32_e32 v163, 0, v40
	v_writelane_b32 v255, s1, 1
	v_cmp_gt_u32_e64 s[0:1], 18, v14
	v_add_u32_e32 v165, 0, v1
	v_add_u32_e32 v166, 0, v3
	v_writelane_b32 v255, s0, 2
	s_mov_b32 s73, 0
	v_mov_b32_e32 v5, v4
	v_writelane_b32 v255, s1, 3
	v_cmp_lt_i32_e64 s[0:1], 18, v12
	v_mov_b32_e32 v7, v4
	v_mov_b32_e32 v56, v4
	v_writelane_b32 v255, s0, 4
	v_mov_b32_e32 v57, v4
	v_mov_b32_e32 v58, v4
	v_writelane_b32 v255, s1, 5
	v_cmp_gt_u32_e64 s[0:1], 19, v14
	v_mov_b32_e32 v59, v4
	s_nop 0
	v_writelane_b32 v255, s0, 6
	s_nop 1
	v_writelane_b32 v255, s1, 7
	v_cmp_lt_i32_e64 s[0:1], 19, v12
	s_nop 1
	v_writelane_b32 v255, s0, 8
	s_nop 1
	v_writelane_b32 v255, s1, 9
	v_cmp_gt_u32_e64 s[0:1], 20, v14
	s_nop 1
	v_writelane_b32 v255, s0, 10
	s_nop 1
	v_writelane_b32 v255, s1, 11
	v_cmp_lt_i32_e64 s[0:1], 32, v12
	s_nop 1
	v_writelane_b32 v255, s0, 12
	s_nop 1
	v_writelane_b32 v255, s1, 13
	v_cmp_gt_u32_e64 s[0:1], 33, v14
	s_nop 1
	v_writelane_b32 v255, s0, 14
	s_nop 1
	v_writelane_b32 v255, s1, 15
	v_cmp_lt_i32_e64 s[0:1], 33, v12
	s_nop 1
	v_writelane_b32 v255, s0, 16
	s_nop 1
	v_writelane_b32 v255, s1, 17
	v_cmp_gt_u32_e64 s[0:1], 34, v14
	s_nop 1
	v_writelane_b32 v255, s0, 18
	s_nop 1
	v_writelane_b32 v255, s1, 19
	v_cmp_lt_i32_e64 s[0:1], 34, v12
	s_nop 1
	v_writelane_b32 v255, s0, 20
	s_nop 1
	v_writelane_b32 v255, s1, 21
	v_cmp_gt_u32_e64 s[0:1], 35, v14
	s_nop 1
	v_writelane_b32 v255, s0, 22
	s_nop 1
	v_writelane_b32 v255, s1, 23
	v_cmp_lt_i32_e64 s[0:1], 35, v12
	v_add_u32_e32 v12, 16, v2
	v_cmp_gt_u32_e64 s[76:77], 18, v12
	v_writelane_b32 v255, s0, 24
	v_cmp_gt_u32_e64 s[80:81], 19, v12
	v_cmp_gt_u32_e64 s[84:85], 20, v12
	v_writelane_b32 v255, s1, 25
	v_cmp_gt_u32_e64 s[0:1], 36, v14
	v_cmp_gt_u32_e64 s[88:89], 33, v12
	v_cmp_gt_u32_e64 s[92:93], 34, v12
	v_writelane_b32 v255, s0, 26
	v_cmp_gt_u32_e64 s[96:97], 35, v12
	v_cmp_gt_u32_e64 s[10:11], 36, v12
	v_writelane_b32 v255, s1, 27
	v_cmp_gt_u32_e64 s[0:1], 49, v14
	v_cmp_gt_u32_e64 s[8:9], 49, v12
	v_cmp_gt_u32_e64 s[6:7], 50, v12
	v_writelane_b32 v255, s0, 28
	v_cmp_gt_u32_e64 s[4:5], 51, v12
	s_nop 0
	v_writelane_b32 v255, s1, 29
	v_cmp_gt_u32_e64 s[0:1], 50, v14
	s_nop 1
	v_writelane_b32 v255, s0, 30
	s_nop 1
	v_writelane_b32 v255, s1, 31
	v_cmp_gt_u32_e64 s[0:1], 51, v14
	s_nop 1
	v_writelane_b32 v255, s0, 32
	s_nop 1
	v_writelane_b32 v255, s1, 33
	v_cmp_gt_u32_e64 s[0:1], 52, v14
	v_mov_b32_e32 v14, v13
	s_nop 0
	v_writelane_b32 v255, s0, 34
	s_nop 1
	v_writelane_b32 v255, s1, 35
	v_cmp_lt_i32_e64 s[0:1], 0, v2
	s_nop 1
	v_writelane_b32 v255, s0, 36
	s_nop 1
	v_writelane_b32 v255, s1, 37
	v_cmp_lt_i32_e64 s[0:1], 1, v2
	s_nop 1
	v_writelane_b32 v255, s0, 38
	s_nop 1
	v_writelane_b32 v255, s1, 39
	v_cmp_lt_i32_e64 s[0:1], 2, v2
	s_nop 1
	v_writelane_b32 v255, s0, 40
	s_nop 1
	v_writelane_b32 v255, s1, 41
	v_cmp_lt_i32_e64 s[0:1], 3, v2
	s_nop 1
	v_writelane_b32 v255, s0, 42
	s_nop 1
	v_writelane_b32 v255, s1, 43
	v_cmp_lt_i32_e64 s[0:1], 16, v2
	v_mul_u32_u24_e32 v2, 0x90, v145
	v_add_u32_e32 v167, v6, v2
	v_and_b32_e32 v252, 8, v216
	v_add_u32_e32 v167, v167, v252
	v_writelane_b32 v255, s0, 44
	v_mov_b32_e32 v6, v4
	s_nop 0
	v_writelane_b32 v255, s1, 45
	v_cmp_gt_u32_e64 s[0:1], 17, v12
	s_nop 1
	v_writelane_b32 v255, s0, 46
	s_nop 1
	v_writelane_b32 v255, s1, 47
	v_cmp_gt_u32_e64 s[0:1], 52, v12
	v_mov_b32_e32 v12, v13
	v_mov_b64_e32 v[78:79], v[14:15]
	v_mov_b64_e32 v[74:75], v[14:15]
	v_mov_b64_e32 v[70:71], v[14:15]
	v_mov_b64_e32 v[66:67], v[14:15]
	v_mov_b64_e32 v[62:63], v[14:15]
	v_mov_b64_e32 v[54:55], v[14:15]
	v_mov_b64_e32 v[50:51], v[14:15]
	v_mov_b64_e32 v[8:9], v[12:13]
	v_mov_b64_e32 v[76:77], v[12:13]
	v_mov_b64_e32 v[72:73], v[12:13]
	v_mov_b64_e32 v[68:69], v[12:13]
	v_mov_b64_e32 v[64:65], v[12:13]
	v_mov_b64_e32 v[60:61], v[12:13]
	v_mov_b64_e32 v[52:53], v[12:13]
	v_mov_b64_e32 v[48:49], v[12:13]
	v_mov_b64_e32 v[10:11], v[14:15]

.LBB0_775:
	v_exp_f32_e32 v80, v80
	v_exp_f32_e32 v81, v81
	v_exp_f32_e32 v82, v82
	v_exp_f32_e32 v83, v83
	v_exp_f32_e32 v4, v92
	v_cvt_pk_bf16_f32 v118, v80, v81
	v_exp_f32_e32 v5, v93
	v_cvt_pk_bf16_f32 v119, v82, v83
	v_mov_b64_e32 v[82:83], s[46:47]
	v_exp_f32_e32 v6, v94
	v_exp_f32_e32 v7, v95
	v_exp_f32_e32 v12, v88
	v_exp_f32_e32 v88, v89
	v_exp_f32_e32 v89, v90
	v_exp_f32_e32 v90, v91
	v_mov_b64_e32 v[80:81], s[44:45]
	v_exp_f32_e32 v84, v84
	v_exp_f32_e32 v85, v85
	v_exp_f32_e32 v86, v86
	v_exp_f32_e32 v87, v87
	v_cvt_pk_bf16_f32 v4, v4, v5
	v_cvt_pk_bf16_f32 v5, v6, v7
	v_cvt_pk_bf16_f32 v6, v12, v88
	v_cvt_pk_bf16_f32 v7, v89, v90
	v_cvt_pk_bf16_f32 v116, v84, v85
	v_cvt_pk_bf16_f32 v117, v86, v87
	v_mfma_f32_16x16x32_bf16 v[56:59], v[80:83], v[4:7], v[56:59]
	v_add_u32_e32 v12, 0x2000, v167
	s_add_i32 s14, s68, -2
	s_cmp_lt_i32 s14, s62
	v_mfma_f32_16x16x32_bf16 v[80:83], v[80:83], v[116:119], v[56:59]
	s_nop 3
	ds_read2_b64 v[56:59], v12 offset0:128 offset1:132
	ds_read2_b64 v[88:91], v12 offset0:136 offset1:140
	v_add_u32_e32 v12, 0x2800, v167
	ds_read2_b64 v[96:99], v12 offset0:160 offset1:164
	ds_read2_b64 v[100:103], v12 offset0:168 offset1:172
	v_add_u32_e32 v12, 0x3000, v167
	ds_read2_b64 v[108:111], v12 offset0:192 offset1:196
	ds_read2_b64 v[120:123], v12 offset0:200 offset1:204
	v_add_u32_e32 v12, 0x3800, v167
	ds_read2_b64 v[124:127], v12 offset0:224 offset1:228
	ds_read2_b64 v[128:131], v12 offset0:232 offset1:236
	s_cselect_b64 s[2:3], -1, 0
	s_cmp_ge_i32 s14, s62
	s_waitcnt lgkmcnt(7)
	v_mfma_f32_16x16x32_bf16 v[76:79], v[56:59], v[104:107], v[76:79]
	v_mfma_f32_16x16x32_bf16 v[56:59], v[56:59], v[4:7], v[60:63]
	s_waitcnt lgkmcnt(6)
	v_mfma_f32_16x16x32_bf16 v[92:95], v[88:91], v[116:119], v[56:59]
	s_waitcnt lgkmcnt(5)
	v_mfma_f32_16x16x32_bf16 v[56:59], v[96:99], v[104:107], v[72:75]
	v_mfma_f32_16x16x32_bf16 v[52:55], v[96:99], v[4:7], v[52:55]
	s_waitcnt lgkmcnt(3)
	v_mfma_f32_16x16x32_bf16 v[48:51], v[108:111], v[4:7], v[48:51]
	v_mfma_f32_16x16x32_bf16 v[84:87], v[88:91], v[112:115], v[76:79]
	v_mfma_f32_16x16x32_bf16 v[88:91], v[100:103], v[112:115], v[56:59]
	v_mfma_f32_16x16x32_bf16 v[100:103], v[100:103], v[116:119], v[52:55]
	v_mfma_f32_16x16x32_bf16 v[52:55], v[108:111], v[104:107], v[68:71]
	s_waitcnt lgkmcnt(2)
	v_mfma_f32_16x16x32_bf16 v[108:111], v[120:123], v[116:119], v[48:51]
	s_waitcnt lgkmcnt(1)
	v_mfma_f32_16x16x32_bf16 v[48:51], v[124:127], v[104:107], v[64:67]
	v_mfma_f32_16x16x32_bf16 v[4:7], v[124:127], v[4:7], v[8:11]
	v_mfma_f32_16x16x32_bf16 v[96:99], v[120:123], v[112:115], v[52:55]
	s_waitcnt lgkmcnt(0)
	v_mfma_f32_16x16x32_bf16 v[104:107], v[128:131], v[112:115], v[48:51]
	v_mfma_f32_16x16x32_bf16 v[112:115], v[128:131], v[116:119], v[4:7]
	s_cbranch_scc1 .LBB0_777
	s_waitcnt vmcnt(3)
	ds_write_b128 v153, v[32:35] offset:18432
	s_waitcnt vmcnt(2)
	ds_write2_b64 v251, v[36:37], v[38:39] offset1:1

.LBB0_796:
	v_exp_f32_e32 v48, v48
	v_exp_f32_e32 v49, v49
	v_exp_f32_e32 v50, v50
	v_exp_f32_e32 v51, v51
	v_exp_f32_e32 v1, v60
	v_cvt_pk_bf16_f32 v174, v48, v49
	v_exp_f32_e32 v2, v61
	v_cvt_pk_bf16_f32 v175, v50, v51
	v_mov_b64_e32 v[50:51], s[46:47]
	v_exp_f32_e32 v3, v62
	v_exp_f32_e32 v12, v63
	v_exp_f32_e32 v14, v56
	v_exp_f32_e32 v15, v57
	v_exp_f32_e32 v56, v58
	v_exp_f32_e32 v57, v59
	v_mov_b64_e32 v[48:49], s[44:45]
	v_exp_f32_e32 v52, v52
	v_exp_f32_e32 v53, v53
	v_exp_f32_e32 v54, v54
	v_exp_f32_e32 v55, v55
	v_cvt_pk_bf16_f32 v168, v1, v2
	v_cvt_pk_bf16_f32 v169, v3, v12
	v_cvt_pk_bf16_f32 v170, v14, v15
	v_cvt_pk_bf16_f32 v171, v56, v57
	v_cvt_pk_bf16_f32 v172, v52, v53
	v_cvt_pk_bf16_f32 v173, v54, v55
	v_mfma_f32_16x16x32_bf16 v[52:55], v[48:51], v[168:171], v[132:135]
	v_add_u32_e32 v1, 0x6800, v167
	v_mfma_f32_16x16x32_bf16 v[56:59], v[48:51], v[172:175], v[52:55]
	ds_read2_b64 v[48:51], v1 offset0:128 offset1:132
	s_nop 4
	ds_read2_b64 v[52:55], v1 offset0:136 offset1:140
	v_add_u32_e32 v1, 0x7000, v167
	ds_read2_b64 v[132:135], v1 offset0:160 offset1:164
	ds_read2_b64 v[176:179], v1 offset0:168 offset1:172
	v_add_u32_e32 v1, 0x7800, v167
	ds_read2_b64 v[182:185], v1 offset0:192 offset1:196
	ds_read2_b64 v[186:189], v1 offset0:200 offset1:204
	v_add_u32_e32 v1, 0x8000, v167
	ds_read2_b64 v[196:199], v1 offset0:224 offset1:228
	ds_read2_b64 v[200:203], v1 offset0:232 offset1:236
	s_waitcnt lgkmcnt(7)
	v_mfma_f32_16x16x32_bf16 v[60:63], v[48:51], v[64:67], v[124:127]
	s_andn2_b64 vcc, exec, s[60:61]
	v_mfma_f32_16x16x32_bf16 v[48:51], v[48:51], v[168:171], v[72:75]
	s_waitcnt lgkmcnt(6)
	v_mfma_f32_16x16x32_bf16 v[76:79], v[52:55], v[128:131], v[60:63]
	v_mfma_f32_16x16x32_bf16 v[60:63], v[52:55], v[172:175], v[48:51]
	s_waitcnt lgkmcnt(5)
	v_mfma_f32_16x16x32_bf16 v[48:51], v[132:135], v[64:67], v[120:123]
	s_waitcnt lgkmcnt(4)
	v_mfma_f32_16x16x32_bf16 v[72:75], v[176:179], v[128:131], v[48:51]
	v_mfma_f32_16x16x32_bf16 v[48:51], v[132:135], v[168:171], v[68:71]
	v_mfma_f32_16x16x32_bf16 v[52:55], v[176:179], v[172:175], v[48:51]
	s_waitcnt lgkmcnt(3)
	v_mfma_f32_16x16x32_bf16 v[48:51], v[182:185], v[64:67], v[116:119]
	s_waitcnt lgkmcnt(1)
	v_mfma_f32_16x16x32_bf16 v[8:11], v[196:199], v[64:67], v[8:11]
	v_mfma_f32_16x16x32_bf16 v[68:71], v[186:189], v[128:131], v[48:51]
	v_mfma_f32_16x16x32_bf16 v[48:51], v[182:185], v[168:171], v[140:143]
	s_waitcnt lgkmcnt(0)
	v_mfma_f32_16x16x32_bf16 v[64:67], v[200:203], v[128:131], v[8:11]
	v_mfma_f32_16x16x32_bf16 v[8:11], v[196:199], v[168:171], v[136:139]
	v_mfma_f32_16x16x32_bf16 v[48:51], v[186:189], v[172:175], v[48:51]
	v_mfma_f32_16x16x32_bf16 v[8:11], v[200:203], v[172:175], v[8:11]
	s_cbranch_vccnz .LBB0_798
	s_waitcnt vmcnt(3)
	ds_write_b128 v153, v[40:43]
	s_waitcnt vmcnt(2)
	ds_write2_b64 v250, v[44:45], v[46:47] offset1:1

.LBB0_809:
	s_and_b64 vcc, exec, s[4:5]
	s_cbranch_vccz .LBB0_715
	v_mov_b32_e32 v16, v216
	s_lshl_b32 s0, s64, 7
	v_and_b32_e32 v185, 15, v16
	v_or_b32_e32 v2, s6, v185
	v_ashrrev_i32_e32 v3, 31, v2
	v_lshlrev_b32_e32 v0, 3, v16
	v_lshlrev_b64 v[4:5], 7, v[2:3]
	v_or_b32_e32 v2, 16, v2
	v_ashrrev_i32_e32 v3, 31, v2
	s_add_u32 s0, s52, s0
	v_ashrrev_i32_e32 v1, 31, v0
	v_bfe_u32 v17, v16, 4, 2
	v_lshlrev_b64 v[2:3], 7, v[2:3]
	s_addc_u32 s1, s53, 0
	v_lshlrev_b64 v[10:11], 1, v[0:1]
	v_lshl_add_u64 v[4:5], s[54:55], 0, v[4:5]
	v_lshlrev_b32_e32 v182, 4, v17
	v_mov_b32_e32 v183, v13
	v_lshl_add_u64 v[2:3], s[54:55], 0, v[2:3]
	v_lshl_add_u64 v[6:7], s[0:1], 0, v[10:11]
	s_or_b32 s0, s64, 64
	v_ashrrev_i32_e32 v196, 3, v16
	v_lshl_add_u64 v[4:5], v[4:5], 0, v[182:183]
	v_lshl_add_u64 v[2:3], v[2:3], 0, v[182:183]
	s_cmp_gt_i32 s62, 1
	global_load_dwordx4 v[84:87], v[4:5], off
	global_load_dwordx4 v[88:91], v[4:5], off offset:64
	global_load_dwordx4 v[92:95], v[2:3], off
	global_load_dwordx4 v[96:99], v[2:3], off offset:64
	v_add_u32_e32 v2, s64, v196
	s_cselect_b32 s0, s0, s64
	v_ashrrev_i32_e32 v3, 31, v2
	v_add_u32_e32 v14, s0, v196
	s_lshl_b32 s0, s0, 7
	v_and_b32_e32 v18, 56, v0
	v_lshlrev_b64 v[2:3], 7, v[2:3]
	v_ashrrev_i32_e32 v15, 31, v14
	s_add_u32 s0, s52, s0
	v_lshl_add_u64 v[2:3], s[50:51], 0, v[2:3]
	v_lshlrev_b32_e32 v12, 1, v18
	v_lshlrev_b64 v[14:15], 7, v[14:15]
	s_addc_u32 s1, s53, 0
	v_lshl_add_u64 v[2:3], v[2:3], 0, v[12:13]
	v_lshl_add_u64 v[14:15], s[50:51], 0, v[14:15]
	v_lshl_add_u64 v[10:11], s[0:1], 0, v[10:11]
	global_load_dwordx4 v[2:5], v[2:3], off
	v_lshl_add_u64 v[14:15], v[14:15], 0, v[12:13]
	global_load_dwordx4 v[6:9], v[6:7], off
	s_nop 0
	global_load_dwordx4 v[104:107], v[10:11], off
	global_load_dwordx4 v[100:103], v[14:15], off
	v_bfe_u32 v10, v16, 1, 6
	v_and_b32_e32 v11, 0x7ffffff0, v196
	v_mul_u32_u24_e32 v10, 0x48, v10
	v_mul_lo_u32 v14, v196, s87
	v_and_or_b32 v11, v0, 8, v11
	v_add_lshl_u32 v14, v14, v18, 1
	v_add_lshl_u32 v10, v11, v10, 1
	v_lshlrev_b32_e32 v184, 3, v17
	v_add_u32_e32 v183, 0, v14
	v_lshrrev_b32_e32 v252, 1, v216
	v_and_b32_e32 v252, 8, v252
	v_add_u32_e32 v197, v10, v252
	v_add_u32_e32 v248, 0x2400, v197
	v_add_u32_e32 v249, 0x6c00, v197
	s_cmp_lt_i32 s62, 1
	s_waitcnt vmcnt(3)
	ds_write_b128 v183, v[2:5]
	s_waitcnt vmcnt(2)
	ds_write2_b64 v248, v[6:7], v[8:9] offset1:1
	s_waitcnt lgkmcnt(0)
	s_barrier
	s_cbranch_scc1 .LBB0_713
	v_mov_b32_e32 v4, 0x480
	v_mov_b32_e32 v6, 0x900
	v_mov_b32_e32 v8, 0xd80
	v_lshl_add_u64 v[188:189], v[0:1], 1, s[52:53]
	v_or_b32_e32 v0, 32, v184
	v_mul_u32_u24_e32 v2, 0x48, v185
	v_mad_u32_u24 v4, v185, s87, v4
	v_mad_u32_u24 v6, v185, s87, v6
	v_mad_u32_u24 v8, v185, s87, v8
	v_lshl_add_u64 v[186:187], s[50:51], 0, v[12:13]
	v_add_u32_e32 v1, 0, v184
	v_add_lshl_u32 v3, v184, v2, 1
	v_add_lshl_u32 v2, v0, v2, 1
	v_add_lshl_u32 v5, v4, v184, 1
	v_add_lshl_u32 v4, v0, v4, 1
	v_add_lshl_u32 v7, v6, v184, 1
	v_add_lshl_u32 v6, v0, v6, 1
	v_add_lshl_u32 v9, v8, v184, 1
	v_add_lshl_u32 v0, v0, v8, 1
	v_mul_u32_u24_e32 v8, 0x90, v185
	s_lshl_b32 s0, s63, 6
	v_mov_b32_e32 v12, v13
	v_mov_b32_e32 v14, v13
	v_mov_b32_e32 v15, v13
	s_sub_i32 s0, s33, s0
	v_add_u32_e32 v198, 0, v3
	v_add_u32_e32 v199, 0, v2
	v_add_u32_e32 v200, 0, v5
	v_add_u32_e32 v201, 0, v4
	v_add_u32_e32 v202, 0, v7
	v_add_u32_e32 v203, 0, v6
	v_add_u32_e32 v204, 0, v9
	v_add_u32_e32 v205, 0, v0
	v_add_u32_e32 v206, v1, v8
	v_and_b32_e32 v252, 8, v216
	v_add_u32_e32 v206, v206, v252
	v_mov_b64_e32 v[82:83], v[14:15]
	v_mov_b64_e32 v[78:79], v[14:15]
	v_mov_b64_e32 v[42:43], v[14:15]
	v_mov_b64_e32 v[38:39], v[14:15]
	v_mov_b64_e32 v[74:75], v[14:15]
	v_mov_b64_e32 v[66:67], v[14:15]
	v_mov_b64_e32 v[58:59], v[14:15]
	v_mov_b64_e32 v[54:55], v[14:15]
	v_mov_b64_e32 v[70:71], v[14:15]
	v_mov_b64_e32 v[62:63], v[14:15]
	v_mov_b64_e32 v[50:51], v[14:15]
	v_mov_b64_e32 v[46:47], v[14:15]
	v_mov_b64_e32 v[34:35], v[14:15]
	v_mov_b64_e32 v[26:27], v[14:15]
	v_mov_b64_e32 v[18:19], v[14:15]
	v_mov_b64_e32 v[4:5], v[12:13]
	v_mov_b64_e32 v[30:31], v[14:15]
	v_mov_b64_e32 v[22:23], v[14:15]
	v_mov_b64_e32 v[8:9], v[12:13]
	v_mov_b64_e32 v[0:1], v[12:13]
	s_add_i32 s10, s0, 0xc0
	s_mov_b32 s14, 0
	v_mov_b32_e32 v207, 0xf149f2ca
	s_mov_b32 s11, 3
	v_mov_b32_e32 v208, 0xf149f2ca
	v_mov_b32_e32 v209, 0xf149f2ca
	v_mov_b32_e32 v210, 0xf149f2ca
	v_mov_b64_e32 v[80:81], v[12:13]
	v_mov_b64_e32 v[76:77], v[12:13]
	v_mov_b64_e32 v[40:41], v[12:13]
	v_mov_b64_e32 v[36:37], v[12:13]
	v_mov_b64_e32 v[72:73], v[12:13]
	v_mov_b64_e32 v[64:65], v[12:13]
	v_mov_b64_e32 v[56:57], v[12:13]
	v_mov_b64_e32 v[52:53], v[12:13]
	v_mov_b64_e32 v[68:69], v[12:13]
	v_mov_b64_e32 v[60:61], v[12:13]
	v_mov_b64_e32 v[48:49], v[12:13]
	v_mov_b64_e32 v[44:45], v[12:13]
	v_mov_b64_e32 v[32:33], v[12:13]
	v_mov_b64_e32 v[24:25], v[12:13]
	v_mov_b64_e32 v[16:17], v[12:13]
	v_mov_b64_e32 v[6:7], v[14:15]
	v_mov_b64_e32 v[28:29], v[12:13]
	v_mov_b64_e32 v[20:21], v[12:13]
	v_mov_b64_e32 v[10:11], v[14:15]
	v_mov_b64_e32 v[2:3], v[14:15]
	s_branch .LBB0_813

.LBB0_827:
	v_exp_f32_e32 v14, v117
	v_exp_f32_e32 v15, v118
	v_exp_f32_e32 v117, v119
	v_exp_f32_e32 v118, v120
	v_exp_f32_e32 v119, v121
	v_exp_f32_e32 v120, v122
	v_exp_f32_e32 v121, v123
	v_exp_f32_e32 v122, v124
	v_exp_f32_e32 v123, v125
	v_exp_f32_e32 v124, v126
	v_exp_f32_e32 v125, v127
	v_exp_f32_e32 v126, v128
	v_exp_f32_e32 v127, v129
	v_cvt_pk_bf16_f32 v118, v118, v119
	v_cvt_pk_bf16_f32 v119, v120, v121
	v_cvt_pk_bf16_f32 v120, v122, v123
	v_cvt_pk_bf16_f32 v121, v124, v125
	v_cvt_pk_bf16_f32 v122, v126, v127
	v_mov_b64_e32 v[126:127], s[46:47]
	v_exp_f32_e32 v12, v116
	v_mov_b64_e32 v[124:125], s[44:45]
	v_exp_f32_e32 v128, v130
	v_exp_f32_e32 v129, v131
	v_cvt_pk_bf16_f32 v116, v12, v14
	v_cvt_pk_bf16_f32 v117, v15, v117
	v_add_u32_e32 v12, 0x2000, v206
	v_cvt_pk_bf16_f32 v123, v128, v129
	v_mfma_f32_16x16x32_bf16 v[36:39], v[124:127], v[116:119], v[36:39]
	s_add_i32 s4, s11, -2
	s_cmp_lt_i32 s4, s62
	s_cselect_b64 s[0:1], -1, 0
	v_mfma_f32_16x16x32_bf16 v[36:39], v[124:127], v[120:123], v[36:39]
	ds_read2_b64 v[124:127], v12 offset0:128 offset1:132
	ds_read2_b64 v[128:131], v12 offset0:136 offset1:140
	v_add_u32_e32 v12, 0x2800, v206
	ds_read2_b64 v[148:151], v12 offset0:160 offset1:164
	ds_read2_b64 v[152:155], v12 offset0:168 offset1:172
	v_add_u32_e32 v12, 0x3000, v206
	ds_read2_b64 v[164:167], v12 offset0:192 offset1:196
	ds_read2_b64 v[168:171], v12 offset0:200 offset1:204
	v_add_u32_e32 v12, 0x3800, v206
	ds_read2_b64 v[172:175], v12 offset0:224 offset1:228
	ds_read2_b64 v[176:179], v12 offset0:232 offset1:236
	s_cmp_ge_i32 s4, s62
	s_waitcnt lgkmcnt(7)
	v_mfma_f32_16x16x32_bf16 v[72:75], v[124:127], v[132:135], v[72:75]
	v_mfma_f32_16x16x32_bf16 v[68:71], v[124:127], v[156:159], v[68:71]
	v_mfma_f32_16x16x32_bf16 v[32:35], v[124:127], v[140:143], v[32:35]
	v_mfma_f32_16x16x32_bf16 v[28:31], v[124:127], v[116:119], v[28:31]
	s_waitcnt lgkmcnt(5)
	v_mfma_f32_16x16x32_bf16 v[64:67], v[148:151], v[132:135], v[64:67]
	v_mfma_f32_16x16x32_bf16 v[60:63], v[148:151], v[156:159], v[60:63]
	v_mfma_f32_16x16x32_bf16 v[24:27], v[148:151], v[140:143], v[24:27]
	v_mfma_f32_16x16x32_bf16 v[20:23], v[148:151], v[116:119], v[20:23]
	s_waitcnt lgkmcnt(3)
	v_mfma_f32_16x16x32_bf16 v[56:59], v[164:167], v[132:135], v[56:59]
	v_mfma_f32_16x16x32_bf16 v[48:51], v[164:167], v[156:159], v[48:51]
	v_mfma_f32_16x16x32_bf16 v[14:17], v[164:167], v[140:143], v[16:19]
	v_mfma_f32_16x16x32_bf16 v[8:11], v[164:167], v[116:119], v[8:11]
	s_waitcnt lgkmcnt(1)
	v_mfma_f32_16x16x32_bf16 v[52:55], v[172:175], v[132:135], v[52:55]
	v_mfma_f32_16x16x32_bf16 v[44:47], v[172:175], v[156:159], v[44:47]
	v_mfma_f32_16x16x32_bf16 v[4:7], v[172:175], v[140:143], v[4:7]
	v_mfma_f32_16x16x32_bf16 v[0:3], v[172:175], v[116:119], v[0:3]
	v_mfma_f32_16x16x32_bf16 v[72:75], v[128:131], v[136:139], v[72:75]
	v_mfma_f32_16x16x32_bf16 v[68:71], v[128:131], v[160:163], v[68:71]
	v_mfma_f32_16x16x32_bf16 v[32:35], v[128:131], v[144:147], v[32:35]
	v_mfma_f32_16x16x32_bf16 v[28:31], v[128:131], v[120:123], v[28:31]
	v_mfma_f32_16x16x32_bf16 v[64:67], v[152:155], v[136:139], v[64:67]
	v_mfma_f32_16x16x32_bf16 v[60:63], v[152:155], v[160:163], v[60:63]
	v_mfma_f32_16x16x32_bf16 v[24:27], v[152:155], v[144:147], v[24:27]
	v_mfma_f32_16x16x32_bf16 v[20:23], v[152:155], v[120:123], v[20:23]
	v_mfma_f32_16x16x32_bf16 v[56:59], v[168:171], v[136:139], v[56:59]
	v_mfma_f32_16x16x32_bf16 v[48:51], v[168:171], v[160:163], v[48:51]
	v_mfma_f32_16x16x32_bf16 v[16:19], v[168:171], v[144:147], v[14:17]
	v_mfma_f32_16x16x32_bf16 v[8:11], v[168:171], v[120:123], v[8:11]
	s_waitcnt lgkmcnt(0)
	v_mfma_f32_16x16x32_bf16 v[52:55], v[176:179], v[136:139], v[52:55]
	v_mfma_f32_16x16x32_bf16 v[44:47], v[176:179], v[160:163], v[44:47]
	v_mfma_f32_16x16x32_bf16 v[4:7], v[176:179], v[144:147], v[4:7]
	v_mfma_f32_16x16x32_bf16 v[0:3], v[176:179], v[120:123], v[0:3]
	s_cbranch_scc1 .LBB0_829
	s_waitcnt vmcnt(2)
	ds_write_b128 v183, v[100:103] offset:18432
	ds_write2_b64 v249, v[104:105], v[106:107] offset1:1

.LBB0_843:
	v_exp_f32_e32 v124, v124
	v_exp_f32_e32 v125, v125
	v_exp_f32_e32 v126, v126
	v_exp_f32_e32 v127, v127
	v_exp_f32_e32 v12, v128
	v_exp_f32_e32 v128, v131
	v_exp_f32_e32 v131, v118
	v_exp_f32_e32 v148, v119
	v_cvt_pk_bf16_f32 v118, v124, v125
	v_cvt_pk_bf16_f32 v119, v126, v127
	v_mov_b64_e32 v[126:127], s[46:47]
	v_exp_f32_e32 v14, v129
	v_exp_f32_e32 v15, v130
	v_mov_b64_e32 v[124:125], s[44:45]
	v_exp_f32_e32 v120, v120
	v_exp_f32_e32 v121, v121
	v_exp_f32_e32 v122, v122
	v_exp_f32_e32 v123, v123
	v_exp_f32_e32 v129, v116
	v_exp_f32_e32 v130, v117
	v_cvt_pk_bf16_f32 v116, v12, v14
	v_cvt_pk_bf16_f32 v117, v15, v128
	v_cvt_pk_bf16_f32 v120, v120, v121
	v_cvt_pk_bf16_f32 v121, v122, v123
	v_mfma_f32_16x16x32_bf16 v[36:39], v[124:127], v[116:119], v[36:39]
	v_cvt_pk_bf16_f32 v122, v129, v130
	v_cvt_pk_bf16_f32 v123, v131, v148
	v_add_u32_e32 v12, 0x6800, v206
	s_nop 0
	v_mfma_f32_16x16x32_bf16 v[36:39], v[124:127], v[120:123], v[36:39]
	ds_read2_b64 v[124:127], v12 offset0:128 offset1:132
	ds_read2_b64 v[128:131], v12 offset0:136 offset1:140
	v_add_u32_e32 v12, 0x7000, v206
	ds_read2_b64 v[148:151], v12 offset0:160 offset1:164
	ds_read2_b64 v[152:155], v12 offset0:168 offset1:172
	v_add_u32_e32 v12, 0x7800, v206
	ds_read2_b64 v[164:167], v12 offset0:192 offset1:196
	ds_read2_b64 v[168:171], v12 offset0:200 offset1:204
	v_add_u32_e32 v12, 0x8000, v206
	ds_read2_b64 v[172:175], v12 offset0:224 offset1:228
	ds_read2_b64 v[176:179], v12 offset0:232 offset1:236
	s_waitcnt lgkmcnt(7)
	v_mfma_f32_16x16x32_bf16 v[72:75], v[124:127], v[132:135], v[72:75]
	s_andn2_b64 vcc, exec, s[2:3]
	v_mfma_f32_16x16x32_bf16 v[68:71], v[124:127], v[156:159], v[68:71]
	v_mfma_f32_16x16x32_bf16 v[32:35], v[124:127], v[140:143], v[32:35]
	v_mfma_f32_16x16x32_bf16 v[28:31], v[124:127], v[116:119], v[28:31]
	s_waitcnt lgkmcnt(5)
	v_mfma_f32_16x16x32_bf16 v[64:67], v[148:151], v[132:135], v[64:67]
	v_mfma_f32_16x16x32_bf16 v[60:63], v[148:151], v[156:159], v[60:63]
	v_mfma_f32_16x16x32_bf16 v[24:27], v[148:151], v[140:143], v[24:27]
	v_mfma_f32_16x16x32_bf16 v[20:23], v[148:151], v[116:119], v[20:23]
	s_waitcnt lgkmcnt(3)
	v_mfma_f32_16x16x32_bf16 v[56:59], v[164:167], v[132:135], v[56:59]
	v_mfma_f32_16x16x32_bf16 v[48:51], v[164:167], v[156:159], v[48:51]
	v_mfma_f32_16x16x32_bf16 v[14:17], v[164:167], v[140:143], v[16:19]
	v_mfma_f32_16x16x32_bf16 v[8:11], v[164:167], v[116:119], v[8:11]
	s_waitcnt lgkmcnt(1)
	v_mfma_f32_16x16x32_bf16 v[52:55], v[172:175], v[132:135], v[52:55]
	v_mfma_f32_16x16x32_bf16 v[44:47], v[172:175], v[156:159], v[44:47]
	v_mfma_f32_16x16x32_bf16 v[4:7], v[172:175], v[140:143], v[4:7]
	v_mfma_f32_16x16x32_bf16 v[0:3], v[172:175], v[116:119], v[0:3]
	v_mfma_f32_16x16x32_bf16 v[72:75], v[128:131], v[136:139], v[72:75]
	v_mfma_f32_16x16x32_bf16 v[68:71], v[128:131], v[160:163], v[68:71]
	v_mfma_f32_16x16x32_bf16 v[32:35], v[128:131], v[144:147], v[32:35]
	v_mfma_f32_16x16x32_bf16 v[28:31], v[128:131], v[120:123], v[28:31]
	v_mfma_f32_16x16x32_bf16 v[64:67], v[152:155], v[136:139], v[64:67]
	v_mfma_f32_16x16x32_bf16 v[60:63], v[152:155], v[160:163], v[60:63]
	v_mfma_f32_16x16x32_bf16 v[24:27], v[152:155], v[144:147], v[24:27]
	v_mfma_f32_16x16x32_bf16 v[20:23], v[152:155], v[120:123], v[20:23]
	v_mfma_f32_16x16x32_bf16 v[56:59], v[168:171], v[136:139], v[56:59]
	v_mfma_f32_16x16x32_bf16 v[48:51], v[168:171], v[160:163], v[48:51]
	v_mfma_f32_16x16x32_bf16 v[16:19], v[168:171], v[144:147], v[14:17]
	v_mfma_f32_16x16x32_bf16 v[8:11], v[168:171], v[120:123], v[8:11]
	s_waitcnt lgkmcnt(0)
	v_mfma_f32_16x16x32_bf16 v[52:55], v[176:179], v[136:139], v[52:55]
	v_mfma_f32_16x16x32_bf16 v[44:47], v[176:179], v[160:163], v[44:47]
	v_mfma_f32_16x16x32_bf16 v[4:7], v[176:179], v[144:147], v[4:7]
	v_mfma_f32_16x16x32_bf16 v[0:3], v[176:179], v[120:123], v[0:3]
	s_cbranch_vccnz .LBB0_812
	s_waitcnt vmcnt(3)
	ds_write_b128 v183, v[108:111]
	s_waitcnt vmcnt(2)
	ds_write2_b64 v248, v[112:113], v[114:115] offset1:1
	s_branch .LBB0_812
